# residual+norm epilogue (first instance): row loads software-pipelined two rows ahead into spare registers with counted waits, instead of one load-wait-store round trip per half row
# speedup vs baseline: 1.0048x; 1.0005x over previous
.LBB0_129:
	s_lshl_b32 s26, s20, 8
	s_ashr_i32 s27, s26, 31
	v_mov_b32_e32 v162, v164
	v_mov_b32_e32 v167, v1
	s_lshl_b64 s[38:39], s[26:27], 2
	s_add_u32 s38, s61, s38
	v_lshlrev_b32_e32 v158, 3, v167
	s_addc_u32 s39, s64, s39
	v_ashrrev_i32_e32 v159, 31, v158
	s_or_b64 s[26:27], s[26:27], s[40:41]
	v_lshl_add_u64 v[78:79], v[158:159], 2, s[38:39]
	v_lshl_add_u64 v[160:161], s[26:27], 0, v[158:159]
	v_lshlrev_b32_e32 v158, 2, v162
	v_add_u32_e32 v168, s52, v162
	s_lshl_b32 s21, s21, 8
	v_lshl_add_u32 v158, v167, 6, v158
	v_xor_b32_e32 v170, 64, v158
	v_xor_b32_e32 v169, 0x80, v158
	v_add_u32_e32 v158, s21, v168
	v_ashrrev_i32_e32 v159, 31, v158
	v_lshlrev_b64 v[162:163], 10, v[158:159]
	v_lshl_add_u64 v[180:181], v[162:163], 0, v[160:161]
	v_lshl_add_u64 v[162:163], v[180:181], 2, s[10:11]
	global_load_dwordx4 v[90:93], v[78:79], off offset:16
	global_load_dwordx4 v[94:97], v[78:79], off
	global_load_dwordx4 v[74:77], v[78:79], off offset:528
	s_nop 0
	global_load_dwordx4 v[78:81], v[78:79], off offset:512
	s_nop 0
	s_mov_b64 s[46:47], 0x10000
	global_load_dwordx4 v[182:185], v[162:163], off offset:16
	global_load_dwordx4 v[186:189], v[162:163], off
	global_load_dwordx4 v[190:193], v[162:163], off offset:528
	global_load_dwordx4 v[194:197], v[162:163], off offset:512
	v_lshl_add_u64 v[248:249], v[162:163], 0, s[46:47]
	global_load_dwordx4 v[198:201], v[248:249], off
	global_load_dwordx4 v[202:205], v[248:249], off offset:16
	global_load_dwordx4 v[206:209], v[248:249], off offset:512
	global_load_dwordx4 v[210:213], v[248:249], off offset:528
	v_lshl_add_u64 v[248:249], v[248:249], 0, s[46:47]
	global_load_dwordx4 v[214:217], v[248:249], off
	global_load_dwordx4 v[218:221], v[248:249], off offset:16
	global_load_dwordx4 v[240:243], v[248:249], off offset:512
	global_load_dwordx4 v[244:247], v[248:249], off offset:528
	v_cmp_eq_u32_e32 vcc, 0, v167
	s_waitcnt vmcnt(8)
	v_pk_add_f32 v[138:139], v[138:139], v[182:183]
	v_pk_add_f32 v[142:143], v[142:143], v[186:187]
	v_mul_f32_e32 v171, v138, v138
	v_mul_f32_e32 v172, v139, v139
	v_pk_add_f32 v[140:141], v[140:141], v[184:185]
	v_fmac_f32_e32 v171, v142, v142
	v_fmac_f32_e32 v172, v143, v143
	v_pk_add_f32 v[144:145], v[144:145], v[188:189]
	v_add_f32_e32 v171, v171, v172
	v_mul_f32_e32 v172, v140, v140
	v_fmac_f32_e32 v172, v144, v144
	v_add_f32_e32 v171, v172, v171
	v_mul_f32_e32 v172, v141, v141
	v_fmac_f32_e32 v172, v145, v145
	global_store_dwordx4 v[162:163], v[142:145], off
	global_store_dwordx4 v[162:163], v[138:141], off offset:16
	v_add_f32_e32 v171, v172, v171
	v_pk_mul_f32 v[144:145], v[96:97], v[144:145]
	v_pk_mul_f32 v[142:143], v[94:95], v[142:143]
	v_pk_mul_f32 v[172:173], v[92:93], v[140:141]
	v_pk_mul_f32 v[140:141], v[90:91], v[138:139]
	v_cvt_pk_bf16_f32 v138, v142, v143
	v_cvt_pk_bf16_f32 v139, v144, v145
	v_cvt_pk_bf16_f32 v140, v140, v141
	v_cvt_pk_bf16_f32 v141, v172, v173
	v_lshl_add_u64 v[172:173], v[180:181], 1, s[14:15]
	global_store_dwordx4 v[172:173], v[138:141], off
	s_nop 0
	v_pk_add_f32 v[130:131], v[130:131], v[190:191]
	v_pk_add_f32 v[134:135], v[134:135], v[194:195]
	v_mul_f32_e32 v138, v130, v130
	v_fmac_f32_e32 v138, v134, v134
	v_mul_f32_e32 v139, v131, v131
	v_pk_add_f32 v[132:133], v[132:133], v[192:193]
	v_add_f32_e32 v138, v171, v138
	v_fmac_f32_e32 v139, v135, v135
	v_pk_add_f32 v[136:137], v[136:137], v[196:197]
	v_add_f32_e32 v138, v139, v138
	v_mul_f32_e32 v139, v132, v132
	v_fmac_f32_e32 v139, v136, v136
	v_add_f32_e32 v138, v139, v138
	v_mul_f32_e32 v139, v133, v133
	v_fmac_f32_e32 v139, v137, v137
	global_store_dwordx4 v[162:163], v[134:137], off offset:512
	global_store_dwordx4 v[162:163], v[130:133], off offset:528
	v_add_f32_e32 v140, v139, v138
	v_pk_mul_f32 v[136:137], v[80:81], v[136:137]
	v_pk_mul_f32 v[134:135], v[78:79], v[134:135]
	v_pk_mul_f32 v[138:139], v[76:77], v[132:133]
	v_pk_mul_f32 v[132:133], v[74:75], v[130:131]
	v_cvt_pk_bf16_f32 v130, v134, v135
	v_cvt_pk_bf16_f32 v131, v136, v137
	v_cvt_pk_bf16_f32 v132, v132, v133
	v_cvt_pk_bf16_f32 v133, v138, v139
	global_store_dwordx4 v[172:173], v[130:133], off offset:256
	ds_bpermute_b32 v130, v170, v140
	s_waitcnt lgkmcnt(0)
	v_add_f32_e32 v130, v140, v130
	ds_bpermute_b32 v131, v169, v130
	s_and_saveexec_b64 s[26:27], vcc
	s_movk_i32 s77, 0x1ff
	s_cbranch_execz .LBB0_131
	v_lshl_add_u32 v132, v168, 4, s65
	s_waitcnt lgkmcnt(0)
	v_add_f32_e32 v130, v130, v131
	ds_write_b32 v132, v130
.LBB0_131:
	s_or_b64 exec, exec, s[26:27]
	v_add_u32_e32 v132, 16, v168
	v_add_u32_e32 v130, s21, v132
	s_waitcnt lgkmcnt(0)
	v_ashrrev_i32_e32 v131, 31, v130
	v_lshlrev_b64 v[134:135], 10, v[130:131]
	v_lshl_add_u64 v[142:143], v[134:135], 0, v[160:161]
	v_lshl_add_u64 v[144:145], v[142:143], 2, s[10:11]
	v_lshl_add_u64 v[248:249], v[248:249], 0, s[46:47]
	global_load_dwordx4 v[182:185], v[248:249], off
	global_load_dwordx4 v[186:189], v[248:249], off offset:16
	global_load_dwordx4 v[190:193], v[248:249], off offset:512
	global_load_dwordx4 v[194:197], v[248:249], off offset:528
	v_lshl_add_u64 v[142:143], v[142:143], 1, s[14:15]
	s_waitcnt vmcnt(14)
	v_pk_add_f32 v[128:129], v[128:129], v[200:201]
	v_pk_add_f32 v[126:127], v[126:127], v[198:199]
	v_pk_add_f32 v[124:125], v[124:125], v[204:205]
	v_pk_add_f32 v[122:123], v[122:123], v[202:203]
	v_pk_mul_f32 v[136:137], v[96:97], v[128:129]
	v_pk_mul_f32 v[134:135], v[94:95], v[126:127]
	v_pk_mul_f32 v[138:139], v[92:93], v[124:125]
	v_pk_mul_f32 v[140:141], v[90:91], v[122:123]
	v_cvt_pk_bf16_f32 v134, v134, v135
	v_cvt_pk_bf16_f32 v135, v136, v137
	v_cvt_pk_bf16_f32 v136, v140, v141
	v_cvt_pk_bf16_f32 v137, v138, v139
	global_store_dwordx4 v[144:145], v[126:129], off
	global_store_dwordx4 v[144:145], v[122:125], off offset:16
	global_store_dwordx4 v[142:143], v[134:137], off
	s_nop 0
	v_mul_f32_e32 v122, v122, v122
	v_mul_f32_e32 v123, v123, v123
	v_mul_f32_e32 v124, v124, v124
	v_fmac_f32_e32 v122, v126, v126
	v_fmac_f32_e32 v123, v127, v127
	v_mul_f32_e32 v125, v125, v125
	v_fmac_f32_e32 v124, v128, v128
	v_add_f32_e32 v122, v122, v123
	v_fmac_f32_e32 v125, v129, v129
	v_add_f32_e32 v122, v124, v122
	v_add_f32_e32 v122, v125, v122
	v_pk_add_f32 v[118:119], v[118:119], v[206:207]
	v_pk_add_f32 v[114:115], v[114:115], v[210:211]
	v_pk_add_f32 v[116:117], v[116:117], v[212:213]
	v_mul_f32_e32 v123, v114, v114
	v_mul_f32_e32 v124, v115, v115
	v_fmac_f32_e32 v123, v118, v118
	v_pk_add_f32 v[120:121], v[120:121], v[208:209]
	v_mul_f32_e32 v125, v116, v116
	v_fmac_f32_e32 v124, v119, v119
	v_add_f32_e32 v122, v122, v123
	v_mul_f32_e32 v126, v117, v117
	v_fmac_f32_e32 v125, v120, v120
	v_add_f32_e32 v122, v124, v122
	v_fmac_f32_e32 v126, v121, v121
	v_add_f32_e32 v122, v125, v122
	v_add_f32_e32 v126, v126, v122
	ds_bpermute_b32 v127, v170, v126
	global_store_dwordx4 v[144:145], v[118:121], off offset:512
	global_store_dwordx4 v[144:145], v[114:117], off offset:528
	v_pk_mul_f32 v[124:125], v[74:75], v[114:115]
	v_pk_mul_f32 v[120:121], v[80:81], v[120:121]
	v_pk_mul_f32 v[118:119], v[78:79], v[118:119]
	s_waitcnt lgkmcnt(0)
	v_add_f32_e32 v114, v126, v127
	ds_bpermute_b32 v115, v169, v114
	v_pk_mul_f32 v[122:123], v[76:77], v[116:117]
	v_cvt_pk_bf16_f32 v116, v118, v119
	v_cvt_pk_bf16_f32 v117, v120, v121
	v_cvt_pk_bf16_f32 v118, v124, v125
	v_cvt_pk_bf16_f32 v119, v122, v123
	global_store_dwordx4 v[142:143], v[116:119], off offset:256
	s_and_saveexec_b64 s[26:27], vcc
	s_cbranch_execz .LBB0_133
	v_lshl_add_u32 v116, v132, 4, s65
	s_waitcnt lgkmcnt(0)
	v_add_f32_e32 v114, v114, v115
	ds_write_b32 v116, v114
.LBB0_133:
	s_or_b64 exec, exec, s[26:27]
	v_add_u32_e32 v116, 32, v168
	v_add_u32_e32 v114, s21, v116
	s_waitcnt lgkmcnt(0)
	v_ashrrev_i32_e32 v115, 31, v114
	v_lshlrev_b64 v[118:119], 10, v[114:115]
	v_lshl_add_u64 v[126:127], v[118:119], 0, v[160:161]
	v_lshl_add_u64 v[128:129], v[126:127], 2, s[10:11]
	s_mov_b64 s[46:47], 0x50000
	v_lshl_add_u64 v[248:249], v[248:249], 0, s[46:47]
	s_mov_b64 s[46:47], 0x10000
	global_load_dwordx4 v[198:201], v[248:249], off
	global_load_dwordx4 v[202:205], v[248:249], off offset:16
	global_load_dwordx4 v[206:209], v[248:249], off offset:512
	global_load_dwordx4 v[210:213], v[248:249], off offset:528
	v_lshl_add_u64 v[126:127], v[126:127], 1, s[14:15]
	s_waitcnt vmcnt(20)
	v_pk_add_f32 v[112:113], v[112:113], v[216:217]
	v_pk_add_f32 v[110:111], v[110:111], v[214:215]
	v_pk_add_f32 v[108:109], v[108:109], v[220:221]
	v_pk_add_f32 v[106:107], v[106:107], v[218:219]
	v_pk_mul_f32 v[120:121], v[96:97], v[112:113]
	v_pk_mul_f32 v[118:119], v[94:95], v[110:111]
	v_pk_mul_f32 v[122:123], v[92:93], v[108:109]
	v_pk_mul_f32 v[124:125], v[90:91], v[106:107]
	v_cvt_pk_bf16_f32 v118, v118, v119
	v_cvt_pk_bf16_f32 v119, v120, v121
	v_cvt_pk_bf16_f32 v120, v124, v125
	v_cvt_pk_bf16_f32 v121, v122, v123
	global_store_dwordx4 v[128:129], v[110:113], off
	global_store_dwordx4 v[128:129], v[106:109], off offset:16
	global_store_dwordx4 v[126:127], v[118:121], off
	s_nop 0
	v_mul_f32_e32 v106, v106, v106
	v_mul_f32_e32 v107, v107, v107
	v_mul_f32_e32 v108, v108, v108
	v_fmac_f32_e32 v106, v110, v110
	v_fmac_f32_e32 v107, v111, v111
	v_mul_f32_e32 v109, v109, v109
	v_fmac_f32_e32 v108, v112, v112
	v_add_f32_e32 v106, v106, v107
	v_fmac_f32_e32 v109, v113, v113
	v_add_f32_e32 v106, v108, v106
	v_add_f32_e32 v106, v109, v106
	v_pk_add_f32 v[102:103], v[102:103], v[240:241]
	v_pk_add_f32 v[98:99], v[98:99], v[244:245]
	v_pk_add_f32 v[100:101], v[100:101], v[246:247]
	v_mul_f32_e32 v107, v98, v98
	v_mul_f32_e32 v108, v99, v99
	v_fmac_f32_e32 v107, v102, v102
	v_pk_add_f32 v[104:105], v[104:105], v[242:243]
	v_mul_f32_e32 v109, v100, v100
	v_fmac_f32_e32 v108, v103, v103
	v_add_f32_e32 v106, v106, v107
	v_mul_f32_e32 v110, v101, v101
	v_fmac_f32_e32 v109, v104, v104
	v_add_f32_e32 v106, v108, v106
	v_fmac_f32_e32 v110, v105, v105
	v_add_f32_e32 v106, v109, v106
	v_add_f32_e32 v110, v110, v106
	ds_bpermute_b32 v111, v170, v110
	global_store_dwordx4 v[128:129], v[102:105], off offset:512
	global_store_dwordx4 v[128:129], v[98:101], off offset:528
	v_pk_mul_f32 v[108:109], v[74:75], v[98:99]
	v_pk_mul_f32 v[104:105], v[80:81], v[104:105]
	v_pk_mul_f32 v[102:103], v[78:79], v[102:103]
	s_waitcnt lgkmcnt(0)
	v_add_f32_e32 v98, v110, v111
	ds_bpermute_b32 v99, v169, v98
	v_pk_mul_f32 v[106:107], v[76:77], v[100:101]
	v_cvt_pk_bf16_f32 v100, v102, v103
	v_cvt_pk_bf16_f32 v101, v104, v105
	v_cvt_pk_bf16_f32 v102, v108, v109
	v_cvt_pk_bf16_f32 v103, v106, v107
	global_store_dwordx4 v[126:127], v[100:103], off offset:256
	s_and_saveexec_b64 s[26:27], vcc
	s_movk_i32 s58, 0x1600
	s_movk_i32 s80, 0x4000
	s_movk_i32 s44, 0x280
	s_cbranch_execz .LBB0_135
	v_lshl_add_u32 v100, v116, 4, s65
	s_waitcnt lgkmcnt(0)
	v_add_f32_e32 v98, v98, v99
	ds_write_b32 v100, v98
.LBB0_135:
	s_or_b64 exec, exec, s[26:27]
	v_add_u32_e32 v100, 48, v168
	v_add_u32_e32 v98, s21, v100
	s_waitcnt lgkmcnt(0)
	v_ashrrev_i32_e32 v99, 31, v98
	v_lshlrev_b64 v[102:103], 10, v[98:99]
	v_lshl_add_u64 v[110:111], v[102:103], 0, v[160:161]
	v_lshl_add_u64 v[112:113], v[110:111], 2, s[10:11]
	v_lshl_add_u64 v[248:249], v[248:249], 0, s[46:47]
	global_load_dwordx4 v[214:217], v[248:249], off
	global_load_dwordx4 v[218:221], v[248:249], off offset:16
	global_load_dwordx4 v[240:243], v[248:249], off offset:512
	global_load_dwordx4 v[244:247], v[248:249], off offset:528
	v_lshl_add_u64 v[110:111], v[110:111], 1, s[14:15]
	s_waitcnt vmcnt(20)
	v_pk_add_f32 v[88:89], v[88:89], v[184:185]
	v_pk_add_f32 v[86:87], v[86:87], v[182:183]
	v_pk_add_f32 v[84:85], v[84:85], v[188:189]
	v_pk_add_f32 v[82:83], v[82:83], v[186:187]
	v_pk_mul_f32 v[104:105], v[96:97], v[88:89]
	v_pk_mul_f32 v[102:103], v[94:95], v[86:87]
	v_pk_mul_f32 v[106:107], v[92:93], v[84:85]
	v_pk_mul_f32 v[108:109], v[90:91], v[82:83]
	v_cvt_pk_bf16_f32 v102, v102, v103
	v_cvt_pk_bf16_f32 v103, v104, v105
	v_cvt_pk_bf16_f32 v104, v108, v109
	v_cvt_pk_bf16_f32 v105, v106, v107
	global_store_dwordx4 v[112:113], v[86:89], off
	global_store_dwordx4 v[112:113], v[82:85], off offset:16
	global_store_dwordx4 v[110:111], v[102:105], off
	s_nop 0
	v_mul_f32_e32 v82, v82, v82
	v_mul_f32_e32 v83, v83, v83
	v_mul_f32_e32 v84, v84, v84
	v_fmac_f32_e32 v82, v86, v86
	v_fmac_f32_e32 v83, v87, v87
	v_mul_f32_e32 v85, v85, v85
	v_fmac_f32_e32 v84, v88, v88
	v_add_f32_e32 v82, v82, v83
	v_fmac_f32_e32 v85, v89, v89
	v_add_f32_e32 v82, v84, v82
	v_add_f32_e32 v82, v85, v82
	v_pk_add_f32 v[70:71], v[70:71], v[190:191]
	v_pk_add_f32 v[66:67], v[66:67], v[194:195]
	v_pk_add_f32 v[68:69], v[68:69], v[196:197]
	v_mul_f32_e32 v83, v66, v66
	v_mul_f32_e32 v84, v67, v67
	v_fmac_f32_e32 v83, v70, v70
	v_pk_add_f32 v[72:73], v[72:73], v[192:193]
	v_mul_f32_e32 v85, v68, v68
	v_fmac_f32_e32 v84, v71, v71
	v_add_f32_e32 v82, v82, v83
	v_mul_f32_e32 v86, v69, v69
	v_fmac_f32_e32 v85, v72, v72
	v_add_f32_e32 v82, v84, v82
	v_fmac_f32_e32 v86, v73, v73
	v_add_f32_e32 v82, v85, v82
	v_add_f32_e32 v86, v86, v82
	ds_bpermute_b32 v87, v170, v86
	global_store_dwordx4 v[112:113], v[70:73], off offset:512
	global_store_dwordx4 v[112:113], v[66:69], off offset:528
	v_pk_mul_f32 v[84:85], v[74:75], v[66:67]
	v_pk_mul_f32 v[72:73], v[80:81], v[72:73]
	v_pk_mul_f32 v[70:71], v[78:79], v[70:71]
	s_waitcnt lgkmcnt(0)
	v_add_f32_e32 v66, v86, v87
	ds_bpermute_b32 v67, v169, v66
	v_pk_mul_f32 v[82:83], v[76:77], v[68:69]
	v_cvt_pk_bf16_f32 v68, v70, v71
	v_cvt_pk_bf16_f32 v69, v72, v73
	v_cvt_pk_bf16_f32 v70, v84, v85
	v_cvt_pk_bf16_f32 v71, v82, v83
	global_store_dwordx4 v[110:111], v[68:71], off offset:256
	s_and_saveexec_b64 s[26:27], vcc
	s_cbranch_execz .LBB0_137
	v_lshl_add_u32 v68, v100, 4, s65
	s_waitcnt lgkmcnt(0)
	v_add_f32_e32 v66, v66, v67
	ds_write_b32 v68, v66
.LBB0_137:
	s_or_b64 exec, exec, s[26:27]
	v_add_u32_e32 v68, 0x80, v168
	v_add_u32_e32 v66, s21, v68
	s_waitcnt lgkmcnt(0)
	v_ashrrev_i32_e32 v67, 31, v66
	v_lshlrev_b64 v[70:71], 10, v[66:67]
	v_lshl_add_u64 v[86:87], v[70:71], 0, v[160:161]
	v_lshl_add_u64 v[88:89], v[86:87], 2, s[10:11]
	v_lshl_add_u64 v[248:249], v[248:249], 0, s[46:47]
	global_load_dwordx4 v[182:185], v[248:249], off
	global_load_dwordx4 v[186:189], v[248:249], off offset:16
	global_load_dwordx4 v[190:193], v[248:249], off offset:512
	global_load_dwordx4 v[194:197], v[248:249], off offset:528
	v_lshl_add_u64 v[86:87], v[86:87], 1, s[14:15]
	s_waitcnt vmcnt(20)
	v_pk_add_f32 v[64:65], v[64:65], v[200:201]
	v_pk_add_f32 v[62:63], v[62:63], v[198:199]
	v_pk_add_f32 v[60:61], v[60:61], v[204:205]
	v_pk_add_f32 v[58:59], v[58:59], v[202:203]
	v_pk_mul_f32 v[72:73], v[96:97], v[64:65]
	v_pk_mul_f32 v[70:71], v[94:95], v[62:63]
	v_pk_mul_f32 v[82:83], v[92:93], v[60:61]
	v_pk_mul_f32 v[84:85], v[90:91], v[58:59]
	v_cvt_pk_bf16_f32 v70, v70, v71
	v_cvt_pk_bf16_f32 v71, v72, v73
	v_cvt_pk_bf16_f32 v72, v84, v85
	v_cvt_pk_bf16_f32 v73, v82, v83
	global_store_dwordx4 v[88:89], v[62:65], off
	global_store_dwordx4 v[88:89], v[58:61], off offset:16
	global_store_dwordx4 v[86:87], v[70:73], off
	s_nop 0
	v_mul_f32_e32 v58, v58, v58
	v_mul_f32_e32 v59, v59, v59
	v_mul_f32_e32 v60, v60, v60
	v_fmac_f32_e32 v58, v62, v62
	v_fmac_f32_e32 v59, v63, v63
	v_mul_f32_e32 v61, v61, v61
	v_fmac_f32_e32 v60, v64, v64
	v_add_f32_e32 v58, v58, v59
	v_fmac_f32_e32 v61, v65, v65
	v_add_f32_e32 v58, v60, v58
	v_add_f32_e32 v58, v61, v58
	v_pk_add_f32 v[54:55], v[54:55], v[206:207]
	v_pk_add_f32 v[50:51], v[50:51], v[210:211]
	v_pk_add_f32 v[52:53], v[52:53], v[212:213]
	v_mul_f32_e32 v59, v50, v50
	v_mul_f32_e32 v60, v51, v51
	v_fmac_f32_e32 v59, v54, v54
	v_pk_add_f32 v[56:57], v[56:57], v[208:209]
	v_mul_f32_e32 v61, v52, v52
	v_fmac_f32_e32 v60, v55, v55
	v_add_f32_e32 v58, v58, v59
	v_mul_f32_e32 v62, v53, v53
	v_fmac_f32_e32 v61, v56, v56
	v_add_f32_e32 v58, v60, v58
	v_fmac_f32_e32 v62, v57, v57
	v_add_f32_e32 v58, v61, v58
	v_add_f32_e32 v62, v62, v58
	ds_bpermute_b32 v63, v170, v62
	global_store_dwordx4 v[88:89], v[54:57], off offset:512
	global_store_dwordx4 v[88:89], v[50:53], off offset:528
	v_pk_mul_f32 v[60:61], v[74:75], v[50:51]
	v_pk_mul_f32 v[56:57], v[80:81], v[56:57]
	v_pk_mul_f32 v[54:55], v[78:79], v[54:55]
	s_waitcnt lgkmcnt(0)
	v_add_f32_e32 v50, v62, v63
	ds_bpermute_b32 v51, v169, v50
	v_pk_mul_f32 v[58:59], v[76:77], v[52:53]
	v_cvt_pk_bf16_f32 v52, v54, v55
	v_cvt_pk_bf16_f32 v53, v56, v57
	v_cvt_pk_bf16_f32 v54, v60, v61
	v_cvt_pk_bf16_f32 v55, v58, v59
	global_store_dwordx4 v[86:87], v[52:55], off offset:256
	s_and_saveexec_b64 s[26:27], vcc
	s_cbranch_execz .LBB0_139
	v_lshl_add_u32 v52, v68, 4, s65
	s_waitcnt lgkmcnt(0)
	v_add_f32_e32 v50, v50, v51
	ds_write_b32 v52, v50
.LBB0_139:
	s_or_b64 exec, exec, s[26:27]
	v_add_u32_e32 v52, 0x90, v168
	v_add_u32_e32 v50, s21, v52
	s_waitcnt lgkmcnt(0)
	v_ashrrev_i32_e32 v51, 31, v50
	v_lshlrev_b64 v[54:55], 10, v[50:51]
	v_lshl_add_u64 v[62:63], v[54:55], 0, v[160:161]
	v_lshl_add_u64 v[64:65], v[62:63], 2, s[10:11]
	v_lshl_add_u64 v[248:249], v[248:249], 0, s[46:47]
	global_load_dwordx4 v[198:201], v[248:249], off
	global_load_dwordx4 v[202:205], v[248:249], off offset:16
	global_load_dwordx4 v[206:209], v[248:249], off offset:512
	global_load_dwordx4 v[210:213], v[248:249], off offset:528
	v_lshl_add_u64 v[62:63], v[62:63], 1, s[14:15]
	s_waitcnt vmcnt(20)
	v_pk_add_f32 v[48:49], v[48:49], v[216:217]
	v_pk_add_f32 v[46:47], v[46:47], v[214:215]
	v_pk_add_f32 v[44:45], v[44:45], v[220:221]
	v_pk_add_f32 v[42:43], v[42:43], v[218:219]
	v_pk_mul_f32 v[56:57], v[96:97], v[48:49]
	v_pk_mul_f32 v[54:55], v[94:95], v[46:47]
	v_pk_mul_f32 v[58:59], v[92:93], v[44:45]
	v_pk_mul_f32 v[60:61], v[90:91], v[42:43]
	v_cvt_pk_bf16_f32 v54, v54, v55
	v_cvt_pk_bf16_f32 v55, v56, v57
	v_cvt_pk_bf16_f32 v56, v60, v61
	v_cvt_pk_bf16_f32 v57, v58, v59
	global_store_dwordx4 v[64:65], v[46:49], off
	global_store_dwordx4 v[64:65], v[42:45], off offset:16
	global_store_dwordx4 v[62:63], v[54:57], off
	s_nop 0
	v_mul_f32_e32 v42, v42, v42
	v_mul_f32_e32 v43, v43, v43
	v_mul_f32_e32 v44, v44, v44
	v_fmac_f32_e32 v42, v46, v46
	v_fmac_f32_e32 v43, v47, v47
	v_mul_f32_e32 v45, v45, v45
	v_fmac_f32_e32 v44, v48, v48
	v_add_f32_e32 v42, v42, v43
	v_fmac_f32_e32 v45, v49, v49
	v_add_f32_e32 v42, v44, v42
	v_add_f32_e32 v42, v45, v42
	v_pk_add_f32 v[38:39], v[38:39], v[240:241]
	v_pk_add_f32 v[34:35], v[34:35], v[244:245]
	v_pk_add_f32 v[36:37], v[36:37], v[246:247]
	v_mul_f32_e32 v43, v34, v34
	v_mul_f32_e32 v44, v35, v35
	v_fmac_f32_e32 v43, v38, v38
	v_pk_add_f32 v[40:41], v[40:41], v[242:243]
	v_mul_f32_e32 v45, v36, v36
	v_fmac_f32_e32 v44, v39, v39
	v_add_f32_e32 v42, v42, v43
	v_mul_f32_e32 v46, v37, v37
	v_fmac_f32_e32 v45, v40, v40
	v_add_f32_e32 v42, v44, v42
	v_fmac_f32_e32 v46, v41, v41
	v_add_f32_e32 v42, v45, v42
	v_add_f32_e32 v46, v46, v42
	ds_bpermute_b32 v47, v170, v46
	global_store_dwordx4 v[64:65], v[38:41], off offset:512
	global_store_dwordx4 v[64:65], v[34:37], off offset:528
	v_pk_mul_f32 v[44:45], v[74:75], v[34:35]
	v_pk_mul_f32 v[40:41], v[80:81], v[40:41]
	v_pk_mul_f32 v[38:39], v[78:79], v[38:39]
	s_waitcnt lgkmcnt(0)
	v_add_f32_e32 v34, v46, v47
	ds_bpermute_b32 v35, v169, v34
	v_pk_mul_f32 v[42:43], v[76:77], v[36:37]
	v_cvt_pk_bf16_f32 v36, v38, v39
	v_cvt_pk_bf16_f32 v37, v40, v41
	v_cvt_pk_bf16_f32 v38, v44, v45
	v_cvt_pk_bf16_f32 v39, v42, v43
	global_store_dwordx4 v[62:63], v[36:39], off offset:256
	s_and_saveexec_b64 s[26:27], vcc
	s_cbranch_execz .LBB0_141
	v_lshl_add_u32 v36, v52, 4, s65
	s_waitcnt lgkmcnt(0)
	v_add_f32_e32 v34, v34, v35
	ds_write_b32 v36, v34
.LBB0_141:
	s_or_b64 exec, exec, s[26:27]
	v_add_u32_e32 v36, 0xa0, v168
	v_add_u32_e32 v34, s21, v36
	s_waitcnt lgkmcnt(0)
	v_ashrrev_i32_e32 v35, 31, v34
	v_lshlrev_b64 v[38:39], 10, v[34:35]
	v_lshl_add_u64 v[46:47], v[38:39], 0, v[160:161]
	v_lshl_add_u64 v[48:49], v[46:47], 2, s[10:11]
	v_lshl_add_u64 v[46:47], v[46:47], 1, s[14:15]
	s_waitcnt vmcnt(16)
	v_pk_add_f32 v[32:33], v[32:33], v[184:185]
	v_pk_add_f32 v[30:31], v[30:31], v[182:183]
	v_pk_add_f32 v[28:29], v[28:29], v[188:189]
	v_pk_add_f32 v[26:27], v[26:27], v[186:187]
	v_pk_mul_f32 v[40:41], v[96:97], v[32:33]
	v_pk_mul_f32 v[38:39], v[94:95], v[30:31]
	v_pk_mul_f32 v[42:43], v[92:93], v[28:29]
	v_pk_mul_f32 v[44:45], v[90:91], v[26:27]
	v_cvt_pk_bf16_f32 v38, v38, v39
	v_cvt_pk_bf16_f32 v39, v40, v41
	v_cvt_pk_bf16_f32 v40, v44, v45
	v_cvt_pk_bf16_f32 v41, v42, v43
	global_store_dwordx4 v[48:49], v[30:33], off
	global_store_dwordx4 v[48:49], v[26:29], off offset:16
	global_store_dwordx4 v[46:47], v[38:41], off
	s_nop 0
	v_mul_f32_e32 v26, v26, v26
	v_mul_f32_e32 v27, v27, v27
	v_mul_f32_e32 v28, v28, v28
	v_fmac_f32_e32 v26, v30, v30
	v_fmac_f32_e32 v27, v31, v31
	v_mul_f32_e32 v29, v29, v29
	v_fmac_f32_e32 v28, v32, v32
	v_add_f32_e32 v26, v26, v27
	v_fmac_f32_e32 v29, v33, v33
	v_add_f32_e32 v26, v28, v26
	v_add_f32_e32 v26, v29, v26
	v_pk_add_f32 v[22:23], v[22:23], v[190:191]
	v_pk_add_f32 v[18:19], v[18:19], v[194:195]
	v_pk_add_f32 v[20:21], v[20:21], v[196:197]
	v_mul_f32_e32 v27, v18, v18
	v_mul_f32_e32 v28, v19, v19
	v_fmac_f32_e32 v27, v22, v22
	v_pk_add_f32 v[24:25], v[24:25], v[192:193]
	v_mul_f32_e32 v29, v20, v20
	v_fmac_f32_e32 v28, v23, v23
	v_add_f32_e32 v26, v26, v27
	v_mul_f32_e32 v30, v21, v21
	v_fmac_f32_e32 v29, v24, v24
	v_add_f32_e32 v26, v28, v26
	v_fmac_f32_e32 v30, v25, v25
	v_add_f32_e32 v26, v29, v26
	v_add_f32_e32 v30, v30, v26
	ds_bpermute_b32 v31, v170, v30
	global_store_dwordx4 v[48:49], v[22:25], off offset:512
	global_store_dwordx4 v[48:49], v[18:21], off offset:528
	v_pk_mul_f32 v[28:29], v[74:75], v[18:19]
	v_pk_mul_f32 v[24:25], v[80:81], v[24:25]
	v_pk_mul_f32 v[22:23], v[78:79], v[22:23]
	s_waitcnt lgkmcnt(0)
	v_add_f32_e32 v18, v30, v31
	ds_bpermute_b32 v19, v169, v18
	v_pk_mul_f32 v[26:27], v[76:77], v[20:21]
	v_cvt_pk_bf16_f32 v20, v22, v23
	v_cvt_pk_bf16_f32 v21, v24, v25
	v_cvt_pk_bf16_f32 v22, v28, v29
	v_cvt_pk_bf16_f32 v23, v26, v27
	global_store_dwordx4 v[46:47], v[20:23], off offset:256
	s_and_saveexec_b64 s[26:27], vcc
	s_cbranch_execz .LBB0_143
	v_lshl_add_u32 v20, v36, 4, s65
	s_waitcnt lgkmcnt(0)
	v_add_f32_e32 v18, v18, v19
	ds_write_b32 v20, v18
.LBB0_143:
	s_or_b64 exec, exec, s[26:27]
	v_add_u32_e32 v20, 0xb0, v168
	v_add_u32_e32 v18, s21, v20
	s_waitcnt lgkmcnt(0)
	v_ashrrev_i32_e32 v19, 31, v18
	v_lshlrev_b64 v[22:23], 10, v[18:19]
	v_lshl_add_u64 v[30:31], v[22:23], 0, v[160:161]
	v_lshl_add_u64 v[32:33], v[30:31], 2, s[10:11]
	v_lshl_add_u64 v[30:31], v[30:31], 1, s[14:15]
	s_waitcnt vmcnt(12)
	v_pk_add_f32 v[16:17], v[16:17], v[200:201]
	v_pk_add_f32 v[14:15], v[14:15], v[198:199]
	v_pk_add_f32 v[12:13], v[12:13], v[204:205]
	v_pk_add_f32 v[10:11], v[10:11], v[202:203]
	v_pk_mul_f32 v[24:25], v[96:97], v[16:17]
	v_pk_mul_f32 v[22:23], v[94:95], v[14:15]
	v_pk_mul_f32 v[26:27], v[92:93], v[12:13]
	v_pk_mul_f32 v[28:29], v[90:91], v[10:11]
	v_cvt_pk_bf16_f32 v22, v22, v23
	v_cvt_pk_bf16_f32 v23, v24, v25
	v_cvt_pk_bf16_f32 v24, v28, v29
	v_cvt_pk_bf16_f32 v25, v26, v27
	global_store_dwordx4 v[32:33], v[14:17], off
	global_store_dwordx4 v[32:33], v[10:13], off offset:16
	global_store_dwordx4 v[30:31], v[22:25], off
	s_nop 0
	v_mul_f32_e32 v10, v10, v10
	v_mul_f32_e32 v11, v11, v11
	v_mul_f32_e32 v12, v12, v12
	v_fmac_f32_e32 v10, v14, v14
	v_fmac_f32_e32 v11, v15, v15
	v_mul_f32_e32 v13, v13, v13
	v_fmac_f32_e32 v12, v16, v16
	v_add_f32_e32 v10, v10, v11
	v_fmac_f32_e32 v13, v17, v17
	v_add_f32_e32 v10, v12, v10
	v_add_f32_e32 v10, v13, v10
	v_pk_add_f32 v[6:7], v[6:7], v[206:207]
	v_pk_add_f32 v[2:3], v[2:3], v[210:211]
	v_pk_add_f32 v[4:5], v[4:5], v[212:213]
	v_mul_f32_e32 v11, v2, v2
	v_mul_f32_e32 v12, v3, v3
	v_fmac_f32_e32 v11, v6, v6
	v_pk_add_f32 v[8:9], v[8:9], v[208:209]
	v_mul_f32_e32 v13, v4, v4
	v_fmac_f32_e32 v12, v7, v7
	v_add_f32_e32 v10, v10, v11
	v_mul_f32_e32 v14, v5, v5
	v_fmac_f32_e32 v13, v8, v8
	v_add_f32_e32 v10, v12, v10
	v_fmac_f32_e32 v14, v9, v9
	v_add_f32_e32 v10, v13, v10
	v_add_f32_e32 v14, v14, v10
	ds_bpermute_b32 v15, v170, v14
	global_store_dwordx4 v[32:33], v[6:9], off offset:512
	global_store_dwordx4 v[32:33], v[2:5], off offset:528
	v_pk_mul_f32 v[12:13], v[74:75], v[2:3]
	v_pk_mul_f32 v[8:9], v[80:81], v[8:9]
	v_pk_mul_f32 v[6:7], v[78:79], v[6:7]
	s_waitcnt lgkmcnt(0)
	v_add_f32_e32 v2, v14, v15
	ds_bpermute_b32 v3, v169, v2
	v_pk_mul_f32 v[10:11], v[76:77], v[4:5]
	v_cvt_pk_bf16_f32 v4, v6, v7
	v_cvt_pk_bf16_f32 v5, v8, v9
	v_cvt_pk_bf16_f32 v6, v12, v13
	v_cvt_pk_bf16_f32 v7, v10, v11
	global_store_dwordx4 v[30:31], v[4:7], off offset:256
	s_and_saveexec_b64 s[26:27], vcc
	s_cbranch_execz .LBB0_145
	v_lshl_add_u32 v4, v20, 4, s65
	s_waitcnt lgkmcnt(0)
	v_add_f32_e32 v2, v2, v3
	ds_write_b32 v4, v2
